# dilated-attention phase: static s_setprio 1 for waves 4-7 during the phase; on top of the attention priority/trim version
# baseline (speedup 1.0000x reference)
; __device__ __forceinline__ void ret_stage(const bf16* proj, const float* rot, int n, int hp, ldsp lds, int tid) {
;     const float* rc = rot; const float* rs = rot + SEQ * 32;
; #pragma unroll
;     for (int i = 0; i < 4; ++i) { const int c = tid + 512 * i, j = c >> 4, cc = c & 15, hsel = cc >> 3, d0 = (cc & 7) * 8; const int pos = n * 128 + j;
;         const u32x4 w = *(const u32x4*)(proj + pj(BKC / 128 + hp, pos) + cc * 8);
;         const f32x4 cs = *(const f32x4*)(rc + pos * 32 + (d0 >> 1)), sn = *(const f32x4*)(rs + pos * 32 + (d0 >> 1));
;         const float sc = 0.125f * expf(-(float)j * ret_lg(2 * hp + hsel));
;         u32x4 o;
;         { const float x0 = bf_lo(w.x), x1 = bf_hi(w.x); o.x = cvt_pk_bf16((x0 * cs.x - x1 * sn.x) * sc, (x1 * cs.x + x0 * sn.x) * sc); }
;         { const float x0 = bf_lo(w.y), x1 = bf_hi(w.y); o.y = cvt_pk_bf16((x0 * cs.y - x1 * sn.y) * sc, (x1 * cs.y + x0 * sn.y) * sc); }
;         { const float x0 = bf_lo(w.z), x1 = bf_hi(w.z); o.z = cvt_pk_bf16((x0 * cs.z - x1 * sn.z) * sc, (x1 * cs.z + x0 * sn.z) * sc); }
;         { const float x0 = bf_lo(w.w), x1 = bf_hi(w.w); o.w = cvt_pk_bf16((x0 * cs.w - x1 * sn.w) * sc, (x1 * cs.w + x0 * sn.w) * sc); }
;         *(LAS u32x4*)(lds + j * TP + cc * 16) = o; }
; #pragma unroll
;     for (int i = 0; i < 8; ++i) { const int c = tid + 512 * i, hsel = c >> 11, j = (c >> 4) & 127, cc = c & 15; const int pos = n * 128 + j;
;         const u32x4 w = *(const u32x4*)(proj + pj(BV / 128 + 2 * hp + hsel, pos) + cc * 8);
;         *(LAS u32x4*)(lds + (1 + hsel) * T128 + j * TP + cc * 16) = w; }
; }
; __device__ __forceinline__ void ret_kv_unit(const bf16* proj, const float* rot, float* kv, int n, int hp, ldsp lds, int tid, int lane, int wave) {
; __global__ void __launch_bounds__(512, 2) fwd_mega(Args a) {
;     ...
;         if (IN(pb + 2)) REP(2) { PHASE_BEGIN
;             const bf16* PROJ = (const bf16*)(ws + WS_PROJ);
;             for (int u = blockIdx.x; u < 256; u += G) ret_kv_unit(PROJ, (const float*)(ws + WS_ROT), (float*)(ws + WS_KV), u >> 2, u & 3, lds, tid, lane, wave);
;             for (int u = blockIdx.x; u < 768; u += G) { const int g = u >> 8, rem = u & 255, h = rem & 7, k = rem >> 3; const int dd = g == 0 ? 1 : (g == 1 ? 4 : 16), nub = 32 / dd;
;                 dil_unit(PROJ, (bf16*)(ws + WS_DO), (float*)(ws + WS_DL), g, h, dd, k / nub, k % nub, lds, tid, lane, wave); }
.LBB0_304:
	s_cmp_le_i32 s44, s24
	s_cselect_b64 s[0:1], -1, 0
	s_cmp_lt_i32 s24, s45
	s_cselect_b64 s[4:5], -1, 0
	s_and_b64 s[0:1], s[0:1], s[4:5]
	s_andn2_b64 vcc, exec, s[0:1]
	v_readlane_b32 s0, v254, 15
	v_readlane_b32 s1, v254, 16
	v_readlane_b32 s4, v251, 6
	s_mul_i32 s4, s4, 7
	v_cndmask_b32_e64 v0, 0, 1, s[0:1]
	v_cmp_ne_u32_e64 s[0:1], 1, v0
	s_add_i32 s30, s4, 4
	s_nop 0
	v_writelane_b32 v251, s0, 10
	s_nop 1
	v_writelane_b32 v251, s1, 11
	s_cbranch_vccnz .LBB0_409
	v_readfirstlane_b32 s100, v196
	s_lshr_b32 s100, s100, 8
	s_cmp_lg_u32 s100, 0
	s_cbranch_scc0 .Ldp_skip
	s_setprio 1
.Ldp_skip:
	v_readlane_b32 s0, v254, 0
	v_readlane_b32 s1, v254, 1
	v_mov_b32_e32 v51, v196
	s_load_dwordx2 s[10:11], s[0:1], 0x78
	v_readfirstlane_b32 s1, v51
	s_ashr_i32 s0, s1, 6
	v_readlane_b32 s4, v251, 10
	v_readlane_b32 s5, v251, 11
	s_waitcnt lgkmcnt(0)
	s_add_u32 s12, s10, 0x11000000
	v_and_b32_e32 v50, 63, v51
	s_addc_u32 s13, s11, 0
	s_and_b64 vcc, exec, s[4:5]
	v_ashrrev_i32_e32 v147, 4, v51
	v_add_u32_e32 v2, 0x200, v51
	s_movk_i32 s4, 0x110
	v_lshlrev_b32_e32 v55, 4, v51
	v_and_b32_e32 v149, 31, v51
	v_and_b32_e32 v53, 16, v51
	v_lshlrev_b32_e32 v54, 2, v50
	v_mul_lo_u32 v52, v147, s4
	v_ashrrev_i32_e32 v152, 4, v2
	s_movk_i32 s14, 0x1000
	s_mov_b32 s15, 0x4800000
	s_cbranch_vccnz .LBB0_308
	v_and_b32_e32 v0, 0x70, v55
	v_and_b32_e32 v3, 15, v51
	v_lshl_add_u64 v[6:7], s[10:11], 0, v[0:1]
	v_add_u32_e32 v0, 0x400, v51
	v_ashrrev_i32_e32 v65, 11, v2
	v_bfe_u32 v66, v2, 4, 7
	v_lshlrev_b32_e32 v4, 3, v3
	v_lshlrev_b32_e32 v5, 4, v3
	v_add_u32_e32 v3, 0x600, v51
	v_mul_i32_i24_e32 v2, 0x8800, v65
	v_mul_u32_u24_e32 v12, 0x110, v66
	v_ashrrev_i32_e32 v67, 11, v0
	v_bfe_u32 v68, v0, 4, 7
	v_ashrrev_i32_e32 v59, 4, v0
	v_add3_u32 v12, 0, v2, v12
	v_mul_i32_i24_e32 v0, 0x8800, v67
	v_mul_u32_u24_e32 v2, 0x110, v68
	v_ashrrev_i32_e32 v69, 11, v3
	v_bfe_u32 v70, v3, 4, 7
	v_add3_u32 v13, 0, v0, v2
	v_mul_i32_i24_e32 v0, 0x8800, v69
	v_mul_u32_u24_e32 v2, 0x110, v70
	v_add3_u32 v14, 0, v0, v2
	v_add_u32_e32 v0, 0x800, v51
	v_ashrrev_i32_e32 v63, 11, v51
	v_bfe_u32 v64, v51, 4, 7
	v_ashrrev_i32_e32 v71, 11, v0
	v_mul_i32_i24_e32 v10, 0x8800, v63
	v_mul_u32_u24_e32 v11, 0x110, v64
	v_mul_i32_i24_e32 v0, 0x8800, v71
	v_add3_u32 v10, 0, v10, v11
	v_add3_u32 v11, 0, v0, v11
	v_add_u32_e32 v0, 0xa00, v51
	v_ashrrev_i32_e32 v72, 11, v0
	v_bfe_u32 v73, v0, 4, 7
	v_mul_i32_i24_e32 v0, 0x8800, v72
	v_mul_u32_u24_e32 v2, 0x110, v73
	v_add3_u32 v15, 0, v0, v2
	v_add_u32_e32 v0, 0xc00, v51
	v_ashrrev_i32_e32 v74, 11, v0
	v_bfe_u32 v75, v0, 4, 7
	v_mul_i32_i24_e32 v0, 0x8800, v74
	v_mul_u32_u24_e32 v2, 0x110, v75
	s_mov_b64 s[4:5], 0x200000
	v_add3_u32 v16, 0, v0, v2
	v_add_u32_e32 v0, 0xe00, v51
	v_lshl_add_u64 v[34:35], v[6:7], 0, s[4:5]
	s_mov_b64 s[4:5], 0x300000
	v_ashrrev_i32_e32 v76, 11, v0
	v_bfe_u32 v77, v0, 4, 7
	v_lshl_add_u64 v[36:37], v[6:7], 0, s[4:5]
	v_mul_i32_i24_e32 v0, 0x8800, v76
	v_mul_u32_u24_e32 v2, 0x110, v77
	s_lshl_b32 s5, s0, 5
	v_ashrrev_i32_e32 v61, 4, v3
	v_add3_u32 v17, 0, v0, v2
	s_ashr_i32 s1, s1, 8
	v_lshrrev_b32_e32 v0, 2, v51
	s_and_b32 s5, s5, 0x60
	v_and_b32_e32 v3, 12, v54
	s_mul_i32 s4, s1, 0x8800
	v_and_b32_e32 v0, 11, v0
	v_or3_b32 v18, v53, s5, v3
	s_add_i32 s4, s4, 0
	v_mul_u32_u24_e32 v2, 0x110, v0
	v_lshlrev_b32_e32 v18, 1, v18
	v_add3_u32 v78, s4, v2, v18
	s_lshl_b32 s4, s1, 6
	v_or3_b32 v2, s4, v53, v3
	s_lshl_b32 s4, s5, 8
	s_movk_i32 s6, 0x110
	s_add_u32 s4, s10, s4
	v_cvt_f32_i32_e32 v57, v147
	v_cvt_f32_i32_e32 v58, v152
	v_cvt_f32_i32_e32 v60, v59
	v_cvt_f32_i32_e32 v62, v61
	v_mad_u32_u24 v19, v0, s6, 0
	s_addc_u32 s5, s11, 0
	v_lshlrev_b32_e32 v0, 2, v149
	v_lshlrev_b32_e32 v18, 1, v2
	v_lshl_add_u64 v[2:3], s[4:5], 0, v[0:1]
	s_mov_b64 s[4:5], 0x35000000
	v_lshlrev_b32_e32 v0, 5, v50
	v_add_u32_e32 v6, 0, v5
	v_mul_lo_u32 v7, v152, s6
	v_mul_lo_u32 v8, v59, s6
	v_mul_lo_u32 v9, v61, s6
	v_lshl_add_u64 v[38:39], v[2:3], 0, s[4:5]
	v_and_b32_e32 v2, 0x700, v0
	v_bfe_u32 v56, v51, 3, 1
	v_add_u32_e32 v79, 0x8800, v78
	v_and_b32_e32 v40, 0x400, v0
	v_mov_b32_e32 v41, v1
	v_or_b32_e32 v42, 0x300, v2
	v_mov_b32_e32 v43, v1
	v_or_b32_e32 v44, 0xb00, v2
	v_mov_b32_e32 v45, v1
	v_or_b32_e32 v46, 0x1300, v2
	v_mov_b32_e32 v47, v1
	v_or_b32_e32 v48, 0x1b00, v2
	v_mov_b32_e32 v49, v1
	v_lshlrev_b32_e32 v0, 1, v4
	v_add_u32_e32 v80, v6, v52
	v_add_u32_e32 v81, v6, v7
	v_add_u32_e32 v82, v6, v8
	v_add_u32_e32 v83, v6, v9
	v_add_u32_e32 v84, v10, v5
	v_add_u32_e32 v85, v12, v5
	v_add_u32_e32 v86, v13, v5
	v_add_u32_e32 v87, v14, v5
	v_add_u32_e32 v88, v11, v5
	v_add_u32_e32 v89, v15, v5
	v_add_u32_e32 v90, v16, v5
	v_add_u32_e32 v91, v17, v5
	v_add_u32_e32 v92, v19, v18
	s_mov_b32 s4, s2

; #define SEAM(k) do { if (IN((k) + 1)) { if (hi > N_PHASES) grid.sync();   else { XcdBarrier xb_; xb_.bar = (unsigned*)(ap->ws); xb_.x = xb_xcc_id(); xb_.st = (volatile LAS unsigned*)(lds_raw_las + LDS_BYTES - 16); xcd_barrier(xb_); } } } while (0)
; __device__ __forceinline__ void xcd_barrier(const XcdBarrier& b) {
;     asm volatile("s_waitcnt vmcnt(0)" ::: "memory");
;     __syncthreads();
;     if (threadIdx.x == 0) {
;         unsigned* bar = b.bar;
;         __builtin_amdgcn_s_waitcnt(0);
;         unsigned nloc = b.st[0], nx = b.st[1];
;         if (nloc == 0u) { xcd_barrier_complete(bar, b.x, nloc, nx); b.st[0] = nloc; b.st[1] = nx; }
; __global__ void __launch_bounds__(512, 2) fwd_mega(Args a) {
;     ...
;             SEAM(pb + 2); }
.LBB0_341:
	s_setprio 0
	s_cmp_lt_i32 s30, s45
	v_readlane_b32 s26, v251, 3
	s_cbranch_scc0 .LBB0_409
	v_readlane_b32 s4, v254, 13
	v_readlane_b32 s5, v254, 14
	s_mov_b64 s[0:1], -1
	s_and_b64 vcc, exec, s[4:5]
	s_cbranch_vccz .LBB0_396
	s_getreg_b32 s0, hwreg(HW_REG_XCC_ID, 0, 4)
	s_waitcnt vmcnt(0)
	s_waitcnt vmcnt(0)
	s_barrier
	s_mov_b64 s[4:5], exec
	v_readlane_b32 s6, v254, 4
	v_readlane_b32 s7, v254, 5
	s_and_b64 s[6:7], s[4:5], s[6:7]
	s_mov_b64 exec, s[6:7]
	s_cbranch_execz .LBB0_395
	v_readlane_b32 s1, v254, 49
	s_waitcnt vmcnt(0) expcnt(0) lgkmcnt(0)
	s_and_b32 s20, s0, 15
	v_mov_b32_e32 v0, s1
	ds_read_b32 v3, v0
	v_readlane_b32 s1, v254, 50
	s_waitcnt lgkmcnt(0)
	v_cmp_ne_u32_e32 vcc, 0, v3
	v_mov_b32_e32 v0, s1
	ds_read_b32 v2, v0
	s_cbranch_vccnz .LBB0_359
	s_add_u32 s0, s10, 0x1000
	s_addc_u32 s1, s11, 0
	s_add_u32 s6, s10, 0x1100
	s_addc_u32 s7, s11, 0
	s_add_u32 s8, s10, 0x1200
	s_addc_u32 s9, s11, 0
	s_add_u32 s12, s10, 0x1300
	s_addc_u32 s13, s11, 0
	s_mov_b32 s21, 1
	s_branch .LBB0_347
